# SGU unit: all statistics loads issued before the first wait; normalise-stage loads issued at unit start
# baseline (speedup 1.0000x reference)
.LBB0_777:
	v_ashrrev_i32_e32 v52, 2, v52
	v_add_u32_e32 v2, s12, v52
	v_ashrrev_i32_e32 v3, 31, v2
	v_lshlrev_b32_e32 v0, 5, v51
	v_lshlrev_b64 v[2:3], 12, v[2:3]
	v_and_b32_e32 v14, 0x60, v0
	v_lshl_add_u64 v[2:3], s[2:3], 0, v[2:3]
	s_lshl_b32 s68, s13, 8
	v_and_or_b32 v124, v52, -16, v50
	v_add_u32_e32 v124, s12, v124
	v_ashrrev_i32_e32 v125, 31, v124
	v_lshlrev_b64 v[124:125], 12, v[124:125]
	v_lshl_add_u64 v[124:125], s[2:3], 0, v[124:125]
	v_lshl_add_u64 v[124:125], v[124:125], 0, s[68:69]
	v_lshrrev_b32_e32 v126, 1, v51
	v_and_b32_e32 v126, 24, v126
	v_mov_b32_e32 v127, 0
	v_lshl_add_u64 v[124:125], v[124:125], 0, v[126:127]
	global_load_dwordx2 v[130:131], v[124:125], off offset:2048
	global_load_dwordx2 v[132:133], v[124:125], off offset:2080
	global_load_dwordx2 v[134:135], v[124:125], off offset:2112
	global_load_dwordx2 v[136:137], v[124:125], off offset:2144
	global_load_dwordx2 v[138:139], v[124:125], off offset:2176
	global_load_dwordx2 v[140:141], v[124:125], off offset:2208
	global_load_dwordx2 v[142:143], v[124:125], off offset:2240
	global_load_dwordx2 v[144:145], v[124:125], off offset:2272
	v_lshl_add_u64 v[2:3], v[2:3], 0, s[68:69]
	v_lshlrev_b32_e32 v0, 1, v14
	s_waitcnt lgkmcnt(0)
	v_lshl_add_u64 v[4:5], v[2:3], 0, v[0:1]
	s_barrier
	v_mov_b64_e32 v[6:7], v[146:147]
	v_mov_b64_e32 v[8:9], v[148:149]
	v_mov_b64_e32 v[10:11], v[150:151]
	v_mov_b64_e32 v[12:13], v[152:153]
	v_lshl_add_u32 v0, v52, 3, 0
	s_add_i32 s4, 0, 0x11400
	v_add_u32_e32 v0, 0x11000, v0
	v_lshlrev_b32_e32 v15, 2, v14
	v_mul_u32_u24_e32 v14, 0x88, v14
	v_lshlrev_b32_e32 v22, 1, v52
	ds_read_b64 v[2:3], v0
	v_add_u32_e32 v0, s4, v15
	v_add_u32_e32 v15, 0, v15
	v_lshlrev_b32_e32 v23, 1, v14
	v_add_u32_e32 v53, 0x11600, v15
	ds_read2_b64 v[14:17], v0 offset1:1
	ds_read2_b64 v[18:21], v0 offset0:2 offset1:3
	v_add3_u32 v54, 0, v22, v23
	v_add3_u32 v55, 0, v23, v22
	ds_read2_b64 v[22:25], v0 offset0:4 offset1:5
	ds_read2_b64 v[26:29], v0 offset0:6 offset1:7
	ds_read2_b64 v[30:33], v53 offset1:1
	ds_read2_b64 v[34:37], v53 offset0:2 offset1:3
	ds_read2_b64 v[38:41], v53 offset0:4 offset1:5
	ds_read2_b64 v[42:45], v53 offset0:6 offset1:7
	v_mov_b64_e32 v[46:47], v[154:155]
	v_mov_b64_e32 v[48:49], v[156:157]
	s_add_i32 s10, s10, s11
	s_cmpk_lt_i32 s10, 0x180
	s_mov_b32 s6, s13
	v_lshlrev_b32_e32 v56, 16, v6
	v_and_b32_e32 v6, 0xffff0000, v6
	v_lshlrev_b32_e32 v57, 16, v7
	v_and_b32_e32 v7, 0xffff0000, v7
	v_lshlrev_b32_e32 v58, 16, v8
	v_and_b32_e32 v8, 0xffff0000, v8
	v_lshlrev_b32_e32 v59, 16, v9
	s_waitcnt lgkmcnt(8)
	v_sub_f32_e32 v56, v56, v2
	v_sub_f32_e32 v6, v6, v2
	v_and_b32_e32 v9, 0xffff0000, v9
	v_lshlrev_b32_e32 v60, 16, v10
	v_and_b32_e32 v10, 0xffff0000, v10
	v_sub_f32_e32 v57, v57, v2
	v_sub_f32_e32 v7, v7, v2
	v_sub_f32_e32 v58, v58, v2
	v_sub_f32_e32 v8, v8, v2
	v_sub_f32_e32 v59, v59, v2
	v_mul_f32_e32 v56, v3, v56
	v_mul_f32_e32 v6, v3, v6
	v_sub_f32_e32 v9, v9, v2
	v_sub_f32_e32 v10, v10, v2
	v_mul_f32_e32 v57, v3, v57
	v_mul_f32_e32 v7, v3, v7
	v_mul_f32_e32 v58, v3, v58
	v_mul_f32_e32 v8, v3, v8
	v_mul_f32_e32 v59, v3, v59
	s_waitcnt lgkmcnt(3)
	v_fma_f32 v14, v14, v56, v30
	v_fma_f32 v6, v15, v6, v31
	v_mul_f32_e32 v9, v3, v9
	v_mul_f32_e32 v10, v3, v10
	v_fma_f32 v15, v57, v16, v32
	v_fmac_f32_e32 v33, v7, v17
	s_waitcnt lgkmcnt(2)
	v_fma_f32 v7, v58, v18, v34
	v_fma_f32 v8, v8, v19, v35
	v_fma_f32 v16, v59, v20, v36
	v_cvt_pk_bf16_f32 v14, v14, v1
	v_cvt_pk_bf16_f32 v6, v6, v1
	v_sub_f32_e32 v60, v60, v2
	v_fmac_f32_e32 v37, v9, v21
	v_cvt_pk_bf16_f32 v15, v15, v1
	v_cvt_pk_bf16_f32 v17, v33, v1
	v_cvt_pk_bf16_f32 v7, v7, v1
	v_cvt_pk_bf16_f32 v8, v8, v1
	v_cvt_pk_bf16_f32 v16, v16, v1
	v_cvt_pk_bf16_f32 v18, v37, v1
	ds_write_b16 v54, v14
	ds_write_b16 v55, v6 offset:272
	ds_write_b16 v54, v15 offset:544
	ds_write_b16 v55, v17 offset:816
	ds_write_b16 v54, v7 offset:1088
	ds_write_b16 v55, v8 offset:1360
	ds_write_b16 v54, v16 offset:1632
	ds_write_b16 v55, v18 offset:1904
	s_waitcnt lgkmcnt(9)
	v_fma_f32 v6, v23, v10, v39
	v_mul_f32_e32 v60, v3, v60
	v_cvt_pk_bf16_f32 v6, v6, v1
	v_fma_f32 v9, v22, v60, v38
	v_cvt_pk_bf16_f32 v7, v9, v1
	ds_write_b16 v55, v6 offset:2448
	v_lshlrev_b32_e32 v6, 16, v11
	ds_write_b16 v54, v7 offset:2176
	v_sub_f32_e32 v6, v6, v2
	v_and_b32_e32 v7, 0xffff0000, v11
	v_mul_f32_e32 v6, v3, v6
	v_sub_f32_e32 v7, v7, v2
	v_fma_f32 v6, v6, v24, v40
	v_mul_f32_e32 v7, v3, v7
	v_fmac_f32_e32 v41, v7, v25
	v_cvt_pk_bf16_f32 v8, v6, v1
	v_mov_b64_e32 v[4:5], v[158:159]
	v_mov_b64_e32 v[6:7], v[160:161]
	ds_write_b16 v54, v8 offset:2720
	v_cvt_pk_bf16_f32 v8, v41, v1
	ds_write_b16 v55, v8 offset:2992
	v_lshlrev_b32_e32 v8, 16, v12
	v_sub_f32_e32 v8, v8, v2
	v_mul_f32_e32 v8, v3, v8
	v_and_b32_e32 v9, 0xffff0000, v12
	s_waitcnt lgkmcnt(12)
	v_fma_f32 v8, v8, v26, v42
	v_sub_f32_e32 v9, v9, v2
	v_mul_f32_e32 v9, v3, v9
	v_cvt_pk_bf16_f32 v8, v8, v1
	v_fma_f32 v9, v9, v27, v43
	ds_write_b16 v54, v8 offset:3264
	v_cvt_pk_bf16_f32 v8, v9, v1
	ds_write_b16 v55, v8 offset:3536
	v_lshlrev_b32_e32 v8, 16, v13
	v_sub_f32_e32 v8, v8, v2
	v_mul_f32_e32 v8, v3, v8
	v_and_b32_e32 v9, 0xffff0000, v13
	v_fma_f32 v8, v8, v28, v44
	v_sub_f32_e32 v9, v9, v2
	v_mul_f32_e32 v9, v3, v9
	v_cvt_pk_bf16_f32 v8, v8, v1
	v_fmac_f32_e32 v45, v9, v29
	ds_write_b16 v54, v8 offset:3808
	v_cvt_pk_bf16_f32 v8, v45, v1
	ds_write_b16 v55, v8 offset:4080
	ds_read2_b64 v[8:11], v0 offset0:8 offset1:9
	ds_read2_b64 v[12:15], v53 offset0:8 offset1:9
	v_lshlrev_b32_e32 v16, 16, v46
	v_sub_f32_e32 v16, v16, v2
	v_mul_f32_e32 v24, v3, v16
	ds_read2_b64 v[16:19], v0 offset0:10 offset1:11
	ds_read2_b64 v[20:23], v53 offset0:10 offset1:11
	s_waitcnt lgkmcnt(2)
	v_fma_f32 v8, v8, v24, v12
	v_and_b32_e32 v12, 0xffff0000, v46
	v_sub_f32_e32 v12, v12, v2
	v_mul_f32_e32 v12, v3, v12
	v_cvt_pk_bf16_f32 v8, v8, v1
	v_fma_f32 v9, v9, v12, v13
	ds_write_b16 v54, v8 offset:4352
	v_cvt_pk_bf16_f32 v8, v9, v1
	ds_write_b16 v55, v8 offset:4624
	v_lshlrev_b32_e32 v8, 16, v47
	v_sub_f32_e32 v8, v8, v2
	v_mul_f32_e32 v8, v3, v8
	v_and_b32_e32 v9, 0xffff0000, v47
	v_fma_f32 v8, v8, v10, v14
	v_sub_f32_e32 v9, v9, v2
	v_mul_f32_e32 v9, v3, v9
	v_cvt_pk_bf16_f32 v8, v8, v1
	v_fmac_f32_e32 v15, v9, v11
	ds_write_b16 v54, v8 offset:4896
	v_cvt_pk_bf16_f32 v8, v15, v1
	ds_write_b16 v55, v8 offset:5168
	v_lshlrev_b32_e32 v8, 16, v48
	v_sub_f32_e32 v8, v8, v2
	v_mul_f32_e32 v8, v3, v8
	v_and_b32_e32 v9, 0xffff0000, v48
	s_waitcnt lgkmcnt(4)
	v_fma_f32 v8, v8, v16, v20
	v_sub_f32_e32 v9, v9, v2
	v_mul_f32_e32 v9, v3, v9
	v_cvt_pk_bf16_f32 v8, v8, v1
	v_fma_f32 v9, v9, v17, v21
	ds_write_b16 v54, v8 offset:5440
	v_cvt_pk_bf16_f32 v8, v9, v1
	ds_write_b16 v55, v8 offset:5712
	v_lshlrev_b32_e32 v8, 16, v49
	v_sub_f32_e32 v8, v8, v2
	v_mul_f32_e32 v8, v3, v8
	v_and_b32_e32 v9, 0xffff0000, v49
	v_fma_f32 v8, v8, v18, v22
	v_sub_f32_e32 v9, v9, v2
	v_mul_f32_e32 v9, v3, v9
	v_cvt_pk_bf16_f32 v8, v8, v1
	v_fmac_f32_e32 v23, v9, v19
	ds_write_b16 v54, v8 offset:5984
	v_cvt_pk_bf16_f32 v8, v23, v1
	ds_write_b16 v55, v8 offset:6256
	ds_read2_b64 v[8:11], v0 offset0:12 offset1:13
	ds_read2_b64 v[12:15], v53 offset0:12 offset1:13
	s_waitcnt vmcnt(0)
	v_lshlrev_b32_e32 v16, 16, v4
	v_sub_f32_e32 v16, v16, v2
	v_mul_f32_e32 v24, v3, v16
	v_and_b32_e32 v4, 0xffff0000, v4
	ds_read2_b64 v[16:19], v0 offset0:14 offset1:15
	ds_read2_b64 v[20:23], v53 offset0:14 offset1:15
	s_waitcnt lgkmcnt(2)
	v_fma_f32 v0, v8, v24, v12
	v_sub_f32_e32 v4, v4, v2
	v_mul_f32_e32 v4, v3, v4
	v_cvt_pk_bf16_f32 v0, v0, v1
	v_fma_f32 v4, v9, v4, v13
	ds_write_b16 v54, v0 offset:6528
	v_cvt_pk_bf16_f32 v0, v4, v1
	ds_write_b16 v55, v0 offset:6800
	v_lshlrev_b32_e32 v0, 16, v5
	v_sub_f32_e32 v0, v0, v2
	v_mul_f32_e32 v0, v3, v0
	v_and_b32_e32 v4, 0xffff0000, v5
	v_fma_f32 v0, v0, v10, v14
	v_sub_f32_e32 v4, v4, v2
	v_mul_f32_e32 v4, v3, v4
	v_cvt_pk_bf16_f32 v0, v0, v1
	v_fmac_f32_e32 v15, v4, v11
	ds_write_b16 v54, v0 offset:7072
	v_cvt_pk_bf16_f32 v0, v15, v1
	ds_write_b16 v55, v0 offset:7344
	v_lshlrev_b32_e32 v0, 16, v6
	v_sub_f32_e32 v0, v0, v2
	v_mul_f32_e32 v0, v3, v0
	v_and_b32_e32 v4, 0xffff0000, v6
	s_waitcnt lgkmcnt(4)
	v_fma_f32 v0, v0, v16, v20
	v_sub_f32_e32 v4, v4, v2
	v_mul_f32_e32 v4, v3, v4
	v_cvt_pk_bf16_f32 v0, v0, v1
	v_fma_f32 v4, v4, v17, v21
	ds_write_b16 v54, v0 offset:7616
	v_cvt_pk_bf16_f32 v0, v4, v1
	ds_write_b16 v55, v0 offset:7888
	v_lshlrev_b32_e32 v0, 16, v7
	v_sub_f32_e32 v0, v0, v2
	v_mul_f32_e32 v0, v3, v0
	v_and_b32_e32 v4, 0xffff0000, v7
	v_and_or_b32 v20, v52, -16, v50
	v_fma_f32 v0, v0, v18, v22
	v_sub_f32_e32 v2, v4, v2
	v_add_u32_e32 v32, s12, v20
	v_mul_f32_e32 v2, v3, v2
	v_cvt_pk_bf16_f32 v0, v0, v1
	v_ashrrev_i32_e32 v33, 31, v32
	v_fmac_f32_e32 v23, v2, v19
	ds_write_b16 v54, v0 offset:8160
	v_cvt_pk_bf16_f32 v0, v23, v1
	v_lshlrev_b64 v[2:3], 12, v[32:33]
	ds_write_b16 v55, v0 offset:8432
	v_lshl_add_u64 v[2:3], s[2:3], 0, v[2:3]
	v_lshrrev_b32_e32 v0, 1, v51
	v_lshl_add_u64 v[2:3], v[2:3], 0, s[68:69]
	v_and_b32_e32 v0, 24, v0
	v_lshl_add_u64 v[18:19], v[2:3], 0, v[0:1]
	s_waitcnt lgkmcnt(0)
	s_barrier
	s_nop 0
	v_mov_b64_e32 v[36:37], v[130:131]
	s_nop 0
	v_mov_b64_e32 v[42:43], v[132:133]
	v_and_b32_e32 v2, 48, v51
	s_nop 0
	v_mov_b64_e32 v[44:45], v[134:135]
	v_add_u32_e32 v2, 0, v2
	s_movk_i32 s2, 0x110
	v_mad_u32_u24 v50, v50, s2, v2
	ds_read_b128 v[10:13], v50
	v_mad_u64_u32 v[34:35], s[2:3], v20, s2, v[2:3]
	ds_read_b128 v[14:17], v50 offset:64
	ds_read_b128 v[6:9], v34 offset:34816
	ds_read_b128 v[2:5], v34 offset:34880
	s_waitcnt lgkmcnt(1)
	v_mfma_f32_16x16x32_bf16 v[10:13], v[10:13], v[6:9], 0
	v_lshl_add_u32 v20, v20, 2, s4
	ds_read_b32 v51, v20 offset:1024
	ds_read_b128 v[20:23], v50 offset:128
	ds_read_b128 v[24:27], v50 offset:192
	s_waitcnt lgkmcnt(3)
	v_mfma_f32_16x16x32_bf16 v[28:31], v[14:17], v[2:5], v[10:13]
	ds_read_b128 v[14:17], v34 offset:34944
	s_nop 1
	ds_read_b128 v[10:13], v34 offset:35008
	s_nop 0
	v_mov_b64_e32 v[46:47], v[136:137]
	v_lshlrev_b64 v[32:33], 11, v[32:33]
	s_waitcnt lgkmcnt(1)
	v_mfma_f32_16x16x32_bf16 v[20:23], v[20:23], v[14:17], v[28:31]
	v_and_b32_e32 v53, 0xffff0000, v37
	s_waitcnt lgkmcnt(0)
	v_mfma_f32_16x16x32_bf16 v[20:23], v[24:27], v[10:13], v[20:23]
	v_lshl_add_u64 v[28:29], s[0:1], 0, v[32:33]
	v_lshl_add_u64 v[40:41], v[28:29], 0, s[68:69]
	ds_read_b128 v[28:31], v50 offset:4352
	v_lshlrev_b32_e32 v24, 16, v36
	ds_read_b128 v[32:35], v50 offset:4480
	s_nop 2
	v_add_f32_e32 v20, v51, v20
	v_mul_f32_e32 v20, v20, v24
	v_add_f32_e32 v21, v51, v21
	v_and_b32_e32 v24, 0xffff0000, v36
	v_mul_f32_e32 v21, v21, v24
	ds_read_b128 v[24:27], v50 offset:4416
	s_waitcnt lgkmcnt(2)
	v_mfma_f32_16x16x32_bf16 v[28:31], v[28:31], v[6:9], 0
	v_cvt_pk_bf16_f32 v48, v20, v21
	v_add_f32_e32 v20, v51, v22
	v_lshlrev_b32_e32 v21, 16, v37
	v_mul_f32_e32 v49, v20, v21
	v_add_f32_e32 v52, v51, v23
	s_waitcnt lgkmcnt(0)
	v_mfma_f32_16x16x32_bf16 v[20:23], v[24:27], v[2:5], v[28:31]
	ds_read_b128 v[36:39], v50 offset:4544
	v_mul_f32_e32 v24, v52, v53
	v_lshl_add_u64 v[26:27], v[40:41], 0, v[0:1]
	s_mov_b64 s[0:1], 0xce84100
	v_cvt_pk_bf16_f32 v49, v49, v24
	v_mfma_f32_16x16x32_bf16 v[22:25], v[32:35], v[14:17], v[20:23]
	ds_read_b128 v[30:33], v50 offset:8768
	v_readlane_b32 s68, v254, 63
	s_nop 0
	v_lshl_add_u64 v[20:21], v[26:27], 0, s[0:1]
	global_store_dwordx2 v[20:21], v[48:49], off offset:1024
	s_nop 0
	v_mov_b64_e32 v[48:49], v[138:139]
	ds_read_b128 v[26:29], v50 offset:8704
	s_waitcnt lgkmcnt(2)
	v_mfma_f32_16x16x32_bf16 v[22:25], v[36:39], v[10:13], v[22:25]
	ds_read_b128 v[34:37], v50 offset:8832
	ds_read_b128 v[38:41], v50 offset:8896
	s_waitcnt lgkmcnt(2)
	v_mfma_f32_16x16x32_bf16 v[26:29], v[26:29], v[6:9], 0
	s_nop 3
	v_add_f32_e32 v0, v51, v22
	v_lshlrev_b32_e32 v22, 16, v42
	v_mul_f32_e32 v0, v0, v22
	v_add_f32_e32 v22, v51, v23
	v_and_b32_e32 v23, 0xffff0000, v42
	v_mul_f32_e32 v22, v22, v23
	v_cvt_pk_bf16_f32 v42, v0, v22
	v_add_f32_e32 v0, v51, v24
	v_lshlrev_b32_e32 v22, 16, v43
	v_mul_f32_e32 v0, v0, v22
	v_add_f32_e32 v22, v51, v25
	v_and_b32_e32 v23, 0xffff0000, v43
	v_mfma_f32_16x16x32_bf16 v[26:29], v[30:33], v[2:5], v[26:29]
	v_mul_f32_e32 v30, v22, v23
	v_cvt_pk_bf16_f32 v43, v0, v30
	global_store_dwordx2 v[20:21], v[42:43], off offset:1056
	s_nop 0
	v_mov_b64_e32 v[42:43], v[140:141]
	s_waitcnt lgkmcnt(1)
	v_mfma_f32_16x16x32_bf16 v[22:25], v[34:37], v[14:17], v[26:29]
	ds_read_b128 v[30:33], v50 offset:13120
	ds_read_b128 v[34:37], v50 offset:13184
	s_nop 0
	ds_read_b128 v[26:29], v50 offset:13056
	s_waitcnt lgkmcnt(3)
	v_mfma_f32_16x16x32_bf16 v[22:25], v[38:41], v[10:13], v[22:25]
	ds_read_b128 v[38:41], v50 offset:13248
	s_waitcnt lgkmcnt(1)
	v_mfma_f32_16x16x32_bf16 v[26:29], v[26:29], v[6:9], 0
	s_nop 4
	v_add_f32_e32 v0, v51, v22
	v_lshlrev_b32_e32 v22, 16, v44
	v_mul_f32_e32 v0, v0, v22
	v_add_f32_e32 v22, v51, v23
	v_and_b32_e32 v23, 0xffff0000, v44
	v_mul_f32_e32 v22, v22, v23
	v_cvt_pk_bf16_f32 v44, v0, v22
	v_add_f32_e32 v0, v51, v24
	v_lshlrev_b32_e32 v22, 16, v45
	v_mul_f32_e32 v0, v0, v22
	v_add_f32_e32 v22, v51, v25
	v_and_b32_e32 v23, 0xffff0000, v45
	v_mfma_f32_16x16x32_bf16 v[26:29], v[30:33], v[2:5], v[26:29]
	v_mul_f32_e32 v30, v22, v23
	v_cvt_pk_bf16_f32 v45, v0, v30
	global_store_dwordx2 v[20:21], v[44:45], off offset:1088
	s_nop 0
	v_mov_b64_e32 v[44:45], v[142:143]
	v_mfma_f32_16x16x32_bf16 v[22:25], v[34:37], v[14:17], v[26:29]
	s_nop 0
	v_mov_b64_e32 v[18:19], v[144:145]
	ds_read_b128 v[30:33], v50 offset:17472
	ds_read_b128 v[34:37], v50 offset:17536
	s_nop 0
	ds_read_b128 v[26:29], v50 offset:17408
	s_waitcnt lgkmcnt(3)
	v_mfma_f32_16x16x32_bf16 v[22:25], v[38:41], v[10:13], v[22:25]
	s_waitcnt lgkmcnt(0)
	v_mfma_f32_16x16x32_bf16 v[26:29], v[26:29], v[6:9], 0
	s_nop 5
	v_add_f32_e32 v0, v51, v22
	v_lshlrev_b32_e32 v22, 16, v46
	v_mul_f32_e32 v0, v0, v22
	v_add_f32_e32 v22, v51, v23
	v_and_b32_e32 v23, 0xffff0000, v46
	v_mul_f32_e32 v22, v22, v23
	v_cvt_pk_bf16_f32 v38, v0, v22
	v_add_f32_e32 v0, v51, v24
	v_lshlrev_b32_e32 v22, 16, v47
	v_mul_f32_e32 v0, v0, v22
	v_add_f32_e32 v39, v51, v25
	ds_read_b128 v[22:25], v50 offset:17600
	v_mfma_f32_16x16x32_bf16 v[26:29], v[30:33], v[2:5], v[26:29]
	v_and_b32_e32 v30, 0xffff0000, v47
	v_mul_f32_e32 v30, v39, v30
	v_cvt_pk_bf16_f32 v39, v0, v30
	v_mfma_f32_16x16x32_bf16 v[26:29], v[34:37], v[14:17], v[26:29]
	ds_read_b128 v[30:33], v50 offset:21760
	ds_read_b128 v[34:37], v50 offset:21888
	global_store_dwordx2 v[20:21], v[38:39], off offset:1120
	s_waitcnt lgkmcnt(2)
	v_mfma_f32_16x16x32_bf16 v[22:25], v[22:25], v[10:13], v[26:29]
	ds_read_b128 v[38:41], v50 offset:21952
	s_nop 1
	ds_read_b128 v[26:29], v50 offset:21824
	s_waitcnt lgkmcnt(3)
	v_mfma_f32_16x16x32_bf16 v[30:33], v[30:33], v[6:9], 0
	s_nop 1
	v_add_f32_e32 v0, v51, v22
	v_lshlrev_b32_e32 v22, 16, v48
	v_mul_f32_e32 v0, v0, v22
	v_add_f32_e32 v22, v51, v23
	v_and_b32_e32 v23, 0xffff0000, v48
	s_waitcnt lgkmcnt(0)
	v_mfma_f32_16x16x32_bf16 v[26:29], v[26:29], v[2:5], v[30:33]
	v_mul_f32_e32 v22, v22, v23
	v_cvt_pk_bf16_f32 v46, v0, v22
	v_add_f32_e32 v0, v51, v24
	v_lshlrev_b32_e32 v22, 16, v49
	v_mul_f32_e32 v0, v0, v22
	v_add_f32_e32 v22, v51, v25
	v_and_b32_e32 v23, 0xffff0000, v49
	v_mul_f32_e32 v30, v22, v23
	v_mfma_f32_16x16x32_bf16 v[22:25], v[34:37], v[14:17], v[26:29]
	v_cvt_pk_bf16_f32 v47, v0, v30
	ds_read_b128 v[30:33], v50 offset:26176
	ds_read_b128 v[34:37], v50 offset:26240
	v_mfma_f32_16x16x32_bf16 v[22:25], v[38:41], v[10:13], v[22:25]
	ds_read_b128 v[26:29], v50 offset:26112
	ds_read_b128 v[38:41], v50 offset:26304
	global_store_dwordx2 v[20:21], v[46:47], off offset:1152
	s_waitcnt lgkmcnt(1)
	v_mfma_f32_16x16x32_bf16 v[26:29], v[26:29], v[6:9], 0
	s_nop 2
	v_add_f32_e32 v0, v51, v22
	v_lshlrev_b32_e32 v22, 16, v42
	v_mul_f32_e32 v0, v0, v22
	v_add_f32_e32 v22, v51, v23
	v_and_b32_e32 v23, 0xffff0000, v42
	v_mfma_f32_16x16x32_bf16 v[26:29], v[30:33], v[2:5], v[26:29]
	v_mul_f32_e32 v22, v22, v23
	v_cvt_pk_bf16_f32 v42, v0, v22
	v_add_f32_e32 v0, v51, v24
	v_lshlrev_b32_e32 v22, 16, v43
	v_mul_f32_e32 v0, v0, v22
	v_add_f32_e32 v22, v51, v25
	v_and_b32_e32 v23, 0xffff0000, v43
	v_mul_f32_e32 v30, v22, v23
	v_mfma_f32_16x16x32_bf16 v[22:25], v[34:37], v[14:17], v[26:29]
	v_cvt_pk_bf16_f32 v43, v0, v30
	ds_read_b128 v[30:33], v50 offset:30528
	ds_read_b128 v[34:37], v50 offset:30592
	s_waitcnt lgkmcnt(2)
	v_mfma_f32_16x16x32_bf16 v[22:25], v[38:41], v[10:13], v[22:25]
	ds_read_b128 v[26:29], v50 offset:30464
	global_store_dwordx2 v[20:21], v[42:43], off offset:1184
	s_waitcnt lgkmcnt(0)
	v_mfma_f32_16x16x32_bf16 v[6:9], v[26:29], v[6:9], 0
	ds_read_b128 v[26:29], v50 offset:30656
	s_nop 2
	v_add_f32_e32 v0, v51, v22
	v_lshlrev_b32_e32 v22, 16, v44
	v_mfma_f32_16x16x32_bf16 v[2:5], v[30:33], v[2:5], v[6:9]
	v_mul_f32_e32 v0, v0, v22
	v_add_f32_e32 v22, v51, v23
	v_and_b32_e32 v23, 0xffff0000, v44
	v_mfma_f32_16x16x32_bf16 v[2:5], v[34:37], v[14:17], v[2:5]
	v_mul_f32_e32 v22, v22, v23
	v_cvt_pk_bf16_f32 v22, v0, v22
	v_add_f32_e32 v0, v51, v24
	s_waitcnt lgkmcnt(0)
	v_mfma_f32_16x16x32_bf16 v[2:5], v[26:29], v[10:13], v[2:5]
	v_lshlrev_b32_e32 v23, 16, v45
	v_mul_f32_e32 v0, v0, v23
	v_add_f32_e32 v6, v51, v25
	v_and_b32_e32 v7, 0xffff0000, v45
	v_mul_f32_e32 v6, v6, v7
	v_cvt_pk_bf16_f32 v23, v0, v6
	s_nop 2
	v_add_f32_e32 v0, v51, v2
	v_lshlrev_b32_e32 v2, 16, v18
	v_mul_f32_e32 v0, v0, v2
	v_add_f32_e32 v2, v51, v3
	v_and_b32_e32 v3, 0xffff0000, v18
	v_mul_f32_e32 v2, v2, v3
	v_cvt_pk_bf16_f32 v2, v0, v2
	v_add_f32_e32 v0, v51, v4
	v_lshlrev_b32_e32 v3, 16, v19
	v_mul_f32_e32 v0, v0, v3
	v_add_f32_e32 v3, v51, v5
	v_and_b32_e32 v4, 0xffff0000, v19
	v_mul_f32_e32 v3, v3, v4
	global_store_dwordx2 v[20:21], v[22:23], off offset:1216
	v_cvt_pk_bf16_f32 v3, v0, v3
	global_store_dwordx2 v[20:21], v[2:3], off offset:1248
	s_barrier
	s_cbranch_scc0 .LBB0_796
.LBB0_778:
	s_lshr_b32 s0, s10, 2
	s_and_b32 s0, s0, 0x1fffff8
	s_and_b32 s1, s10, 7
	s_or_b32 s4, s0, s1
	s_mov_b64 s[0:1], s[86:87]
	v_mbcnt_lo_u32_b32 v51, -1, 0
	v_mbcnt_hi_u32_b32 v51, -1, v51
	s_add_u32 s2, s0, 0x9e84100
	v_add_u32_e32 v52, s75, v51
	s_addc_u32 s3, s1, 0
	s_lshl_b32 s12, s4, 7
	v_ashrrev_i32_e32 v53, 4, v52
	v_add_u32_e32 v18, s12, v53
	v_ashrrev_i32_e32 v19, 31, v18
	v_and_b32_e32 v50, 15, v51
	v_lshlrev_b64 v[2:3], 12, v[18:19]
	v_lshl_add_u64 v[2:3], s[2:3], 0, v[2:3]
	v_lshlrev_b32_e32 v0, 4, v50
	s_mov_b32 s7, 0x3727c5ac
	v_lshl_add_u64 v[14:15], v[2:3], 0, v[0:1]
	v_ashrrev_i32_e32 v98, 2, v52
	v_add_u32_e32 v98, s12, v98
	v_ashrrev_i32_e32 v99, 31, v98
	v_lshlrev_b64 v[98:99], 12, v[98:99]
	v_lshl_add_u64 v[98:99], s[2:3], 0, v[98:99]
	s_bfe_u32 s100, s10, 0x20003
	s_lshl_b32 s100, s100, 8
	s_mov_b32 s101, 0
	v_lshl_add_u64 v[98:99], v[98:99], 0, s[100:101]
	v_lshlrev_b32_e32 v116, 5, v51
	v_and_b32_e32 v116, 0x60, v116
	v_lshlrev_b32_e32 v116, 1, v116
	v_mov_b32_e32 v117, 0
	v_lshl_add_u64 v[98:99], v[98:99], 0, v[116:117]
	global_load_dwordx4 v[146:149], v[98:99], off offset:3072
	global_load_dwordx4 v[150:153], v[98:99], off offset:3088
	global_load_dwordx4 v[154:157], v[98:99], off offset:3104
	global_load_dwordx4 v[158:161], v[98:99], off offset:3120
	global_load_dwordx4 v[2:5], v[14:15], off offset:3072
	global_load_dwordx4 v[6:9], v[14:15], off offset:3328
	global_load_dwordx4 v[10:13], v[14:15], off offset:3584
	s_nop 0
	global_load_dwordx4 v[14:17], v[14:15], off offset:3840
	v_lshlrev_b32_e32 v19, 2, v51
	v_bitop3_b32 v57, v19, 4, v220 bitop3:0x6c
	v_add_u32_e32 v20, 32, v18
	v_add_u32_e32 v22, 64, v18
	v_add_u32_e32 v18, 0x60, v18
	v_bitop3_b32 v56, v19, 8, v220 bitop3:0x6c
	v_bitop3_b32 v55, v19, 16, v220 bitop3:0x6c
	v_bitop3_b32 v54, v19, 32, v220 bitop3:0x6c
	v_ashrrev_i32_e32 v21, 31, v20
	v_ashrrev_i32_e32 v23, 31, v22
	v_ashrrev_i32_e32 v19, 31, v18
	v_lshlrev_b64 v[20:21], 12, v[20:21]
	v_lshlrev_b64 v[22:23], 12, v[22:23]
	v_lshlrev_b64 v[18:19], 12, v[18:19]
	v_lshl_add_u64 v[20:21], s[2:3], 0, v[20:21]
	v_lshl_add_u64 v[22:23], s[2:3], 0, v[22:23]
	v_readlane_b32 s4, v254, 18
	v_cmp_eq_u32_e32 vcc, 0, v50
	v_lshl_add_u64 v[92:93], v[20:21], 0, v[0:1]
	v_lshl_add_u64 v[94:95], v[22:23], 0, v[0:1]
	v_lshl_add_u64 v[96:97], s[2:3], 0, v[18:19]
	v_lshl_add_u64 v[96:97], v[96:97], 0, v[0:1]
	global_load_dwordx4 v[46:49], v[92:93], off offset:3072
	global_load_dwordx4 v[42:45], v[92:93], off offset:3328
	global_load_dwordx4 v[38:41], v[92:93], off offset:3584
	global_load_dwordx4 v[34:37], v[92:93], off offset:3840
	global_load_dwordx4 v[30:33], v[94:95], off offset:3072
	global_load_dwordx4 v[26:29], v[94:95], off offset:3328
	global_load_dwordx4 v[22:25], v[94:95], off offset:3584
	global_load_dwordx4 v[18:21], v[94:95], off offset:3840
	global_load_dwordx4 v[100:103], v[96:97], off offset:3072
	global_load_dwordx4 v[104:107], v[96:97], off offset:3328
	global_load_dwordx4 v[108:111], v[96:97], off offset:3584
	global_load_dwordx4 v[112:115], v[96:97], off offset:3840
	s_waitcnt vmcnt(12)
	v_lshlrev_b32_e32 v59, 16, v2
	v_and_b32_e32 v60, 0xffff0000, v2
	v_lshlrev_b32_e32 v61, 16, v3
	v_and_b32_e32 v62, 0xffff0000, v3
	v_add_f32_e32 v2, v59, v60
	v_lshlrev_b32_e32 v63, 16, v4
	v_and_b32_e32 v64, 0xffff0000, v4
	v_add_f32_e32 v3, v61, v62
	v_add_f32_e32 v2, 0, v2
	v_lshlrev_b32_e32 v65, 16, v5
	v_and_b32_e32 v66, 0xffff0000, v5
	v_add_f32_e32 v4, v63, v64
	v_add_f32_e32 v2, v3, v2
	v_lshlrev_b32_e32 v67, 16, v6
	v_and_b32_e32 v68, 0xffff0000, v6
	v_add_f32_e32 v5, v65, v66
	v_add_f32_e32 v2, v4, v2
	v_lshlrev_b32_e32 v69, 16, v7
	v_and_b32_e32 v70, 0xffff0000, v7
	v_add_f32_e32 v6, v67, v68
	v_add_f32_e32 v2, v5, v2
	v_lshlrev_b32_e32 v71, 16, v8
	v_and_b32_e32 v72, 0xffff0000, v8
	v_add_f32_e32 v7, v69, v70
	v_add_f32_e32 v2, v6, v2
	v_lshlrev_b32_e32 v73, 16, v9
	v_and_b32_e32 v74, 0xffff0000, v9
	v_add_f32_e32 v8, v71, v72
	v_add_f32_e32 v2, v7, v2
	v_lshlrev_b32_e32 v75, 16, v10
	v_and_b32_e32 v76, 0xffff0000, v10
	v_add_f32_e32 v9, v73, v74
	v_add_f32_e32 v2, v8, v2
	v_lshlrev_b32_e32 v77, 16, v11
	v_and_b32_e32 v78, 0xffff0000, v11
	v_add_f32_e32 v10, v75, v76
	v_add_f32_e32 v2, v9, v2
	v_lshlrev_b32_e32 v79, 16, v12
	v_and_b32_e32 v80, 0xffff0000, v12
	v_add_f32_e32 v11, v77, v78
	v_add_f32_e32 v2, v10, v2
	v_lshlrev_b32_e32 v81, 16, v13
	v_and_b32_e32 v82, 0xffff0000, v13
	v_add_f32_e32 v12, v79, v80
	v_add_f32_e32 v2, v11, v2
	v_lshlrev_b32_e32 v83, 16, v14
	v_and_b32_e32 v84, 0xffff0000, v14
	v_add_f32_e32 v13, v81, v82
	v_add_f32_e32 v2, v12, v2
	v_lshlrev_b32_e32 v85, 16, v15
	v_and_b32_e32 v86, 0xffff0000, v15
	v_add_f32_e32 v14, v83, v84
	v_add_f32_e32 v2, v13, v2
	v_lshlrev_b32_e32 v87, 16, v16
	v_and_b32_e32 v88, 0xffff0000, v16
	v_add_f32_e32 v15, v85, v86
	v_add_f32_e32 v2, v14, v2
	v_lshlrev_b32_e32 v89, 16, v17
	v_and_b32_e32 v90, 0xffff0000, v17
	v_add_f32_e32 v16, v87, v88
	v_add_f32_e32 v2, v15, v2
	v_add_f32_e32 v17, v89, v90
	v_add_f32_e32 v2, v16, v2
	v_add_f32_e32 v8, v17, v2
	s_nop 1
	v_mov_b32_dpp v9, v8 quad_perm:[1,0,3,2] row_mask:0xf bank_mask:0xf
	s_waitcnt lgkmcnt(0)
	v_add_f32_e32 v0, v8, v9
	s_nop 1
	v_mov_b32_dpp v8, v0 quad_perm:[2,3,0,1] row_mask:0xf bank_mask:0xf
	s_waitcnt lgkmcnt(0)
	v_add_f32_e32 v0, v0, v8
	s_nop 1
	v_mov_b32_dpp v4, v0 row_half_mirror row_mask:0xf bank_mask:0xf
	s_waitcnt lgkmcnt(0)
	v_add_f32_e32 v0, v0, v4
	s_nop 1
	v_mov_b32_dpp v58, v0 row_mirror row_mask:0xf bank_mask:0xf
	s_waitcnt lgkmcnt(0)
	v_add_f32_e32 v58, v0, v58
	v_fmac_f32_e32 v60, 0xbb000000, v58
	v_fmac_f32_e32 v59, 0xbb000000, v58
	v_fmac_f32_e32 v62, 0xbb000000, v58
	v_mul_f32_e32 v0, v60, v60
	v_fmac_f32_e32 v61, 0xbb000000, v58
	v_fmac_f32_e32 v0, v59, v59
	v_mul_f32_e32 v59, v62, v62
	v_fmac_f32_e32 v59, v61, v61
	v_fmac_f32_e32 v64, 0xbb000000, v58
	v_add_f32_e32 v0, v0, v59
	v_fmac_f32_e32 v63, 0xbb000000, v58
	v_mul_f32_e32 v59, v64, v64
	v_fmac_f32_e32 v59, v63, v63
	v_fmac_f32_e32 v66, 0xbb000000, v58
	v_add_f32_e32 v0, v59, v0
	v_fmac_f32_e32 v65, 0xbb000000, v58
	v_mul_f32_e32 v59, v66, v66
	v_fmac_f32_e32 v59, v65, v65
	v_fmac_f32_e32 v68, 0xbb000000, v58
	v_add_f32_e32 v0, v59, v0
	v_fmac_f32_e32 v67, 0xbb000000, v58
	v_mul_f32_e32 v59, v68, v68
	v_fmac_f32_e32 v59, v67, v67
	v_fmac_f32_e32 v70, 0xbb000000, v58
	v_add_f32_e32 v0, v59, v0
	v_fmac_f32_e32 v69, 0xbb000000, v58
	v_mul_f32_e32 v59, v70, v70
	v_fmac_f32_e32 v59, v69, v69
	v_fmac_f32_e32 v72, 0xbb000000, v58
	v_add_f32_e32 v0, v59, v0
	v_fmac_f32_e32 v71, 0xbb000000, v58
	v_mul_f32_e32 v59, v72, v72
	v_fmac_f32_e32 v59, v71, v71
	v_fmac_f32_e32 v74, 0xbb000000, v58
	v_add_f32_e32 v0, v59, v0
	v_fmac_f32_e32 v73, 0xbb000000, v58
	v_mul_f32_e32 v59, v74, v74
	v_fmac_f32_e32 v59, v73, v73
	v_fmac_f32_e32 v76, 0xbb000000, v58
	v_add_f32_e32 v0, v59, v0
	v_fmac_f32_e32 v75, 0xbb000000, v58
	v_mul_f32_e32 v59, v76, v76
	v_fmac_f32_e32 v59, v75, v75
	v_fmac_f32_e32 v78, 0xbb000000, v58
	v_add_f32_e32 v0, v59, v0
	v_fmac_f32_e32 v77, 0xbb000000, v58
	v_mul_f32_e32 v59, v78, v78
	v_fmac_f32_e32 v59, v77, v77
	v_fmac_f32_e32 v80, 0xbb000000, v58
	v_add_f32_e32 v0, v59, v0
	v_fmac_f32_e32 v79, 0xbb000000, v58
	v_mul_f32_e32 v59, v80, v80
	v_fmac_f32_e32 v59, v79, v79
	v_fmac_f32_e32 v82, 0xbb000000, v58
	v_add_f32_e32 v0, v59, v0
	v_fmac_f32_e32 v81, 0xbb000000, v58
	v_mul_f32_e32 v59, v82, v82
	v_fmac_f32_e32 v59, v81, v81
	v_fmac_f32_e32 v84, 0xbb000000, v58
	v_add_f32_e32 v0, v59, v0
	v_fmac_f32_e32 v83, 0xbb000000, v58
	v_mul_f32_e32 v59, v84, v84
	v_fmac_f32_e32 v59, v83, v83
	v_fmac_f32_e32 v86, 0xbb000000, v58
	v_add_f32_e32 v0, v59, v0
	v_fmac_f32_e32 v85, 0xbb000000, v58
	v_mul_f32_e32 v59, v86, v86
	v_fmac_f32_e32 v59, v85, v85
	v_fmac_f32_e32 v88, 0xbb000000, v58
	v_add_f32_e32 v0, v59, v0
	v_fmac_f32_e32 v87, 0xbb000000, v58
	v_mul_f32_e32 v59, v88, v88
	v_fmac_f32_e32 v59, v87, v87
	v_fmac_f32_e32 v90, 0xbb000000, v58
	v_add_f32_e32 v0, v59, v0
	v_fmac_f32_e32 v89, 0xbb000000, v58
	v_mul_f32_e32 v59, v90, v90
	v_fmac_f32_e32 v59, v89, v89
	v_add_f32_e32 v0, v59, v0
	s_nop 1
	v_mov_b32_dpp v59, v0 quad_perm:[1,0,3,2] row_mask:0xf bank_mask:0xf
	s_waitcnt lgkmcnt(0)
	v_add_f32_e32 v0, v0, v59
	s_nop 1
	v_mov_b32_dpp v59, v0 quad_perm:[2,3,0,1] row_mask:0xf bank_mask:0xf
	s_waitcnt lgkmcnt(0)
	v_add_f32_e32 v0, v0, v59
	s_nop 1
	v_mov_b32_dpp v59, v0 row_half_mirror row_mask:0xf bank_mask:0xf
	s_waitcnt lgkmcnt(0)
	v_add_f32_e32 v59, v0, v59
	s_nop 1
	v_mov_b32_dpp v60, v59 row_mirror row_mask:0xf bank_mask:0xf
	v_lshl_add_u32 v0, v53, 3, s4
	s_and_saveexec_b64 s[4:5], vcc
	s_cbranch_execz .LBB0_780
	s_waitcnt lgkmcnt(0)
	v_add_f32_e32 v59, v59, v60
	v_mov_b32_e32 v60, s7
	v_fmamk_f32 v59, v59, 0x3b000000, v60
	v_rsq_f32_e32 v59, v59
	v_mul_f32_e32 v58, 0x3b000000, v58
	ds_write_b64 v0, v[58:59]
